# attention: one static s_setprio 1 for waves 4-7 of each workgroup (timing only)
# speedup vs baseline: 1.0017x; 1.0017x over previous
; __global__ void __launch_bounds__(512, 2) mega(Args args) {
;     ...
;             for (int u = blockIdx.x; u < 1024 + 16; u += G) {
;                 size_t qoff, koff; int seq;
;                 if (u < 1024) { const int pair = u >> 8, b = pair >> 1, kvh = pair & 1, hh = (u >> 6) & 3, qb = u & 63, head = kvh * 4 + hh;
;                     qoff = ((size_t)b * SEQ + (size_t)qb * 256) * 1024 + head * 128; koff = (size_t)(b * 2 + kvh) * SKV * 128; seq = SKV; }
;                 else { const int jx = u - 1024, b = jx >> 3, head = jx & 7, kvh = head >> 2;
;                     qoff = ((size_t)NLAT + (size_t)b * CTXL) * 1024 + head * 128; koff = ((size_t)(b * 2 + kvh) * SKV + SEQ) * 128; seq = CTXL; }
;                 __syncthreads();
;     ...
;                 attn::attn_dense_body<attn::bf16>(QR + qoff, KR + koff, VR + koff, OB + qoff, seq, (char*)lds_raw);
.LBB0_175:
	v_readfirstlane_b32 s42, v188
	s_nop 1
	s_cmp_lt_u32 s42, 0x100
	s_cbranch_scc1 .Lattn_prio_done
	s_setprio 1

; __global__ void __launch_bounds__(512, 2) mega(Args args) {
;     ...
;             for (int u = blockIdx.x; u < 1024 + 16; u += G) {
;                 size_t qoff, koff; int seq;
;                 if (u < 1024) { const int pair = u >> 8, b = pair >> 1, kvh = pair & 1, hh = (u >> 6) & 3, qb = u & 63, head = kvh * 4 + hh;
;                     qoff = ((size_t)b * SEQ + (size_t)qb * 256) * 1024 + head * 128; koff = (size_t)(b * 2 + kvh) * SKV * 128; seq = SKV; }
;                 else { const int jx = u - 1024, b = jx >> 3, head = jx & 7, kvh = head >> 2;
;                     qoff = ((size_t)NLAT + (size_t)b * CTXL) * 1024 + head * 128; koff = ((size_t)(b * 2 + kvh) * SKV + SEQ) * 128; seq = CTXL; }
;                 __syncthreads();
;     ...
;                 attn::attn_dense_body<attn::bf16>(QR + qoff, KR + koff, VR + koff, OB + qoff, seq, (char*)lds_raw);
;     ...
;             }
.Lattn_exit:
	s_setprio 0
	s_branch .LBB0_168
